# diff-attn: K-fragment prefetch + exp2 moved into PV MFMA gaps + role-split staging
# speedup vs baseline: 1.0022x; 1.0006x over previous
; __device__ __forceinline__ int v_st(int k, int c) { const int kk = (k & ~0xC) | ((k & 4) << 1) | ((k & 8) >> 1); return ((kk >> 3) * 4 + (c >> 5)) * 512 + ((kk & 7) * 32 + (c & 31)) * 2; }
; __device__ __forceinline__ int v_rd_base(int lane) { return ((lane & 3) << 3) | (((lane >> 2) & 3) << 6) | (((lane >> 4) & 1) << 5) | (((lane >> 5) & 1) << 8); }
; #define SLOAD(i, k0) do { sr_[i].vs0 = ld8(&Vg[(long)((k0) + sr) * LDP + sc]); sr_[i].vs1 = ld8(&Vg[(long)((k0) + 32 + sr) * LDP + sc]); \
;     sr_[i].ks0 = ld8(&Kg[(long)((k0) + sr) * LDP + sc]); sr_[i].ks1 = ld8(&Kg[(long)((k0) + 32 + sr) * LDP + sc]); } while (0)
; #define SWRITE(off, i) do { *(bf16x8*)(V_lds + (off) + vst0) = sr_[i].vs0;          \
;     *(bf16x8*)(V_lds + (off) + vst1) = sr_[i].vs1; int kc = sc * 2;               \
;     *(bf16x8*)(K_lds + (off) + KSWZ(sr, kc)) = sr_[i].ks0;                       \
;     *(bf16x8*)(K_lds + (off) + KSWZ(32 + sr, kc)) = sr_[i].ks1; } while (0)
; template <int MODE, int ORD> ...
;     ...
;   const bf16* Qw = Qb + (long)(wq * 32 + r32) * LDP + cst * 64 + hi * 8;
; #pragma unroll
;   for (int d0 = 0; d0 < ND0; ++d0) qr[d0] = scale_bf16x8(ld8(Qw + d0 * 16), C);
;   const int qpos = qpos0 + wq * 32 + r32;
;   const int qw0 = qpos0 + wq * 32;
;   const int cboff = cst * 128;
;   int sr = tid >> 4, sc = (tid & 15) * 8, vst0 = v_st(sr, sc), vst1 = v_st(32 + sr, sc);
;   int vb0 = (int)(uintptr_t)V_lds + v_rd_base(lane);
;   const bf16* Kg = Kh + (long)kbeg * LDP; const bf16* Vg = Vh + (long)kbeg * LDP;
;   struct { bf16x8 vs0, vs1, ks0, ks1; } sr_[1];
;     ...
;   SLOAD(SE, 0); asm volatile("s_waitcnt vmcnt(0)" ::: "memory"); SWRITE(0, SE); __syncthreads();
.LBB0_157:
	s_or_b64 exec, exec, s[0:1]
	s_lshl_b32 s68, s6, 7
	s_add_u32 s6, s10, s68
	s_addc_u32 s7, s11, 0
	s_mul_i32 s0, s7, 0x2400
	s_mul_hi_u32 s1, s6, 0x2400
	s_add_i32 s1, s1, s0
	s_mul_i32 s0, s6, 0x2400
	s_add_u32 s0, s20, s0
	s_addc_u32 s1, s21, s1
	s_lshl_b32 s78, s80, 8
	s_add_u32 s0, s0, s78
	s_mul_i32 s18, s11, 0x2400
	s_mul_hi_u32 s19, s10, 0x2400
	s_addc_u32 s1, s1, 0
	s_add_i32 s19, s19, s18
	s_mul_i32 s18, s10, 0x2400
	s_add_u32 s18, s20, s18
	s_addc_u32 s19, s21, s19
	s_add_u32 s18, s18, s78
	s_addc_u32 s19, s19, 0
	s_add_u32 s42, s18, 0x1000
	s_addc_u32 s43, s19, 0
	s_and_b32 s66, s62, 3
	v_and_b32_e32 v184, 31, v40
	s_lshl_b32 s79, s66, 5
	v_or_b32_e32 v0, s79, v184
	v_mul_u32_u24_e32 v0, 0x1200, v0
	s_ashr_i32 s64, s63, 8
	v_lshlrev_b32_e32 v204, 1, v0
	v_lshl_add_u64 v[0:1], s[0:1], 0, v[204:205]
	s_lshl_b32 s0, s64, 6
	v_bfe_u32 v185, v40, 5, 1
	s_ashr_i32 s1, s0, 31
	v_lshl_add_u64 v[0:1], s[0:1], 1, v[0:1]
	v_lshlrev_b32_e32 v204, 4, v185
	v_lshl_add_u64 v[4:5], v[0:1], 0, v[204:205]
	global_load_dwordx4 v[0:3], v[4:5], off
	v_ashrrev_i32_e32 v38, 4, v40
	v_lshlrev_b32_e32 v16, 3, v40
	v_add_u32_e32 v17, 32, v38
	v_and_b32_e32 v41, 0x78, v16
	v_lshlrev_b32_e32 v19, 4, v40
	v_and_b32_e32 v20, 0xfffff0, v38
	v_lshlrev_b32_e32 v21, 1, v38
	v_lshrrev_b32_e32 v22, 1, v38
	v_and_b32_e32 v23, 3, v38
	v_and_b32_e32 v47, 0x70, v19
	v_and_or_b32 v19, v21, 8, v20
	v_and_or_b32 v20, v22, 4, v23
	v_and_b32_e32 v22, 0xfffff0, v17
	v_lshlrev_b32_e32 v23, 1, v17
	v_and_b32_e32 v18, 0x70, v40
	v_bfe_u32 v16, v16, 5, 2
	v_lshlrev_b32_e32 v24, 8, v38
	v_lshlrev_b32_e32 v21, 1, v41
	v_lshrrev_b32_e32 v19, 1, v19
	v_and_or_b32 v22, v23, 8, v22
	v_bitop3_b32 v191, v21, v24, v18 bitop3:0xde
	v_lshlrev_b32_e32 v20, 6, v20
	v_and_b32_e32 v23, 48, v21
	v_lshlrev_b32_e32 v39, 8, v184
	s_add_i32 s69, 0, 0x18800
	v_lshl_or_b32 v48, s64, 7, v204
	v_xad_u32 v188, v48, v47, v39
	v_add_u32_e32 v42, 0, v191
	s_or_b32 s92, s79, s68
	s_cmpk_lt_u32 s92, 0xbf
	s_cselect_b64 s[48:49], -1, 0
	v_readlane_b32 s34, v255, 35
	s_mov_b64 s[56:57], -1
	s_and_b64 vcc, exec, s[48:49]
	v_lshlrev_b32_e32 v197, 2, v185
	s_waitcnt vmcnt(0)
	v_lshlrev_b32_e32 v6, 16, v0
	v_and_b32_e32 v0, 0xffff0000, v0
	v_lshlrev_b32_e32 v7, 16, v1
	v_and_b32_e32 v1, 0xffff0000, v1
	v_lshlrev_b32_e32 v8, 16, v2
	v_and_b32_e32 v2, 0xffff0000, v2
	v_lshlrev_b32_e32 v9, 16, v3
	v_and_b32_e32 v3, 0xffff0000, v3
	v_mul_f32_e32 v0, 0x3e38aa3b, v0
	v_mul_f32_e32 v1, 0x3e38aa3b, v1
	v_mul_f32_e32 v2, 0x3e38aa3b, v2
	v_mul_f32_e32 v3, 0x3e38aa3b, v3
	v_mul_f32_e32 v6, 0x3e38aa3b, v6
	v_mul_f32_e32 v7, 0x3e38aa3b, v7
	v_mul_f32_e32 v8, 0x3e38aa3b, v8
	v_mul_f32_e32 v9, 0x3e38aa3b, v9
	v_cvt_pk_bf16_f32 v128, v6, v0
	v_cvt_pk_bf16_f32 v129, v7, v1
	v_cvt_pk_bf16_f32 v130, v8, v2
	v_cvt_pk_bf16_f32 v131, v9, v3
	global_load_dwordx4 v[0:3], v[4:5], off offset:32
	s_waitcnt vmcnt(0)
	v_lshlrev_b32_e32 v6, 16, v0
	v_and_b32_e32 v0, 0xffff0000, v0
	v_lshlrev_b32_e32 v7, 16, v1
	v_and_b32_e32 v1, 0xffff0000, v1
	v_lshlrev_b32_e32 v8, 16, v2
	v_and_b32_e32 v2, 0xffff0000, v2
	v_lshlrev_b32_e32 v9, 16, v3
	v_and_b32_e32 v3, 0xffff0000, v3
	v_mul_f32_e32 v0, 0x3e38aa3b, v0
	v_mul_f32_e32 v1, 0x3e38aa3b, v1
	v_mul_f32_e32 v2, 0x3e38aa3b, v2
	v_mul_f32_e32 v3, 0x3e38aa3b, v3
	v_mul_f32_e32 v6, 0x3e38aa3b, v6
	v_mul_f32_e32 v7, 0x3e38aa3b, v7
	v_mul_f32_e32 v8, 0x3e38aa3b, v8
	v_mul_f32_e32 v9, 0x3e38aa3b, v9
	v_cvt_pk_bf16_f32 v132, v6, v0
	v_cvt_pk_bf16_f32 v133, v7, v1
	v_cvt_pk_bf16_f32 v134, v8, v2
	v_cvt_pk_bf16_f32 v135, v9, v3
	global_load_dwordx4 v[0:3], v[4:5], off offset:64
	s_waitcnt vmcnt(0)
	v_lshlrev_b32_e32 v6, 16, v0
	v_and_b32_e32 v0, 0xffff0000, v0
	v_lshlrev_b32_e32 v7, 16, v1
	v_and_b32_e32 v1, 0xffff0000, v1
	v_lshlrev_b32_e32 v8, 16, v2
	v_and_b32_e32 v2, 0xffff0000, v2
	v_lshlrev_b32_e32 v9, 16, v3
	v_and_b32_e32 v3, 0xffff0000, v3
	v_mul_f32_e32 v0, 0x3e38aa3b, v0
	v_mul_f32_e32 v1, 0x3e38aa3b, v1
	v_mul_f32_e32 v2, 0x3e38aa3b, v2
	v_mul_f32_e32 v3, 0x3e38aa3b, v3
	v_mul_f32_e32 v6, 0x3e38aa3b, v6
	v_mul_f32_e32 v7, 0x3e38aa3b, v7
	v_mul_f32_e32 v8, 0x3e38aa3b, v8
	v_mul_f32_e32 v9, 0x3e38aa3b, v9
	v_cvt_pk_bf16_f32 v136, v6, v0
	v_cvt_pk_bf16_f32 v137, v7, v1
	v_cvt_pk_bf16_f32 v138, v8, v2
	v_cvt_pk_bf16_f32 v139, v9, v3
	global_load_dwordx4 v[0:3], v[4:5], off offset:96
	v_mad_i64_i32 v[4:5], s[0:1], v38, s73, 0
	v_mad_i64_i32 v[6:7], s[0:1], v17, s73, 0
	v_or_b32_e32 v4, v4, v41
	v_or_b32_e32 v6, v6, v41
	v_lshlrev_b64 v[4:5], 1, v[4:5]
	v_lshlrev_b64 v[6:7], 1, v[6:7]
	v_lshl_add_u64 v[8:9], s[18:19], 0, v[4:5]
	v_lshl_add_u64 v[12:13], s[18:19], 0, v[6:7]
	v_lshl_add_u64 v[4:5], s[42:43], 0, v[4:5]
	v_lshl_add_u64 v[6:7], s[42:43], 0, v[6:7]
	v_lshlrev_b32_e32 v17, 8, v17
	v_bitop3_b32 v192, v21, v17, v18 bitop3:0xde
	v_or_b32_e32 v17, v19, v16
	v_lshrrev_b32_e32 v18, 1, v22
	v_lshlrev_b32_e32 v17, 9, v17
	v_or_b32_e32 v16, v18, v16
	v_lshlrev_b32_e32 v16, 9, v16
	v_or3_b32 v193, v17, v20, v23
	v_or3_b32 v194, v16, v20, v23
	v_add_u32_e32 v44, 0, v193
	v_mov_b32_e32 v16, s69
	v_add_u32_e32 v43, 0, v192
	v_add_u32_e32 v45, 0, v194
	s_waitcnt vmcnt(0)
	v_lshlrev_b32_e32 v10, 16, v0
	v_and_b32_e32 v0, 0xffff0000, v0
	v_lshlrev_b32_e32 v11, 16, v1
	v_and_b32_e32 v1, 0xffff0000, v1
	v_lshlrev_b32_e32 v14, 16, v2
	v_and_b32_e32 v2, 0xffff0000, v2
	v_lshlrev_b32_e32 v15, 16, v3
	v_and_b32_e32 v3, 0xffff0000, v3
	v_mul_f32_e32 v10, 0x3e38aa3b, v10
	v_mul_f32_e32 v0, 0x3e38aa3b, v0
	v_mul_f32_e32 v11, 0x3e38aa3b, v11
	v_mul_f32_e32 v1, 0x3e38aa3b, v1
	v_mul_f32_e32 v14, 0x3e38aa3b, v14
	v_mul_f32_e32 v2, 0x3e38aa3b, v2
	v_mul_f32_e32 v15, 0x3e38aa3b, v15
	v_mul_f32_e32 v3, 0x3e38aa3b, v3
	v_cvt_pk_bf16_f32 v140, v10, v0
	v_cvt_pk_bf16_f32 v141, v11, v1
	v_cvt_pk_bf16_f32 v142, v14, v2
	v_cvt_pk_bf16_f32 v143, v15, v3
	s_cmp_lt_i32 s62, 4
	s_cbranch_scc1 .Lmy_p0A
	s_mov_b32 s100, 0xfffdc000
	s_mov_b32 s101, -1
	v_lshl_add_u64 v[234:235], v[4:5], 0, s[100:101]
	v_add_u32_e32 v238, 0xfffff000, v193
	s_branch .Lmy_p0J
; #define SLOAD(i, k0) do { sr_[i].vs0 = ld8(&Vg[(long)((k0) + sr) * LDP + sc]); sr_[i].vs1 = ld8(&Vg[(long)((k0) + 32 + sr) * LDP + sc]); \
;     sr_[i].ks0 = ld8(&Kg[(long)((k0) + sr) * LDP + sc]); sr_[i].ks1 = ld8(&Kg[(long)((k0) + 32 + sr) * LDP + sc]); } while (0)
; #define SWRITE(off, i) do { *(bf16x8*)(V_lds + (off) + vst0) = sr_[i].vs0;          \
;     *(bf16x8*)(V_lds + (off) + vst1) = sr_[i].vs1; int kc = sc * 2;               \
;     *(bf16x8*)(K_lds + (off) + KSWZ(sr, kc)) = sr_[i].ks0;                       \
;     *(bf16x8*)(K_lds + (off) + KSWZ(32 + sr, kc)) = sr_[i].ks1; } while (0)
; #define SETBE(t) do { TCLS(t); const float bt_ = near_ ? 0.f : ((rmax_ <= -128) ? bL : bR); \
;     if (bt_ != be_cur) { const float d_ = bt_ - be_cur; _Pragma("unroll") for (int r = 0; r < 16; ++r) negm[r] += d_; be_cur = bt_; } } while (0)
; template <int MODE, int ORD> ...
;     ...
;   SLOAD(SE, 0); asm volatile("s_waitcnt vmcnt(0)" ::: "memory"); SWRITE(0, SE); __syncthreads();
;   bL = tab[0]; bR = tab[256];
;   SETBE(0); qkt<ND0>(pA0, pA1, K_lds, qr, r32, hi, cboff, negm); BIAS(pA0, pA1, 0); partialSM2<MODE == 0>(pA0, pA1, m_reg, negm, alA);
.Lmy_p0A:
	s_mov_b64 s[100:101], 0x800
	v_lshl_add_u64 v[234:235], v[8:9], 0, s[100:101]
	v_add_u32_e32 v238, 0x4000, v191
.Lmy_p0J:
	s_mov_b64 s[100:101], 0x24000
	v_lshl_add_u64 v[236:237], v[234:235], 0, s[100:101]
	s_mov_b32 s100, 0x48000
	v_lshl_add_u64 v[240:241], v[234:235], 0, s[100:101]
	s_mov_b32 s100, 0x6c000
	v_lshl_add_u64 v[242:243], v[234:235], 0, s[100:101]
	global_load_dwordx4 v[0:3], v[234:235], off
	global_load_dwordx4 v[4:7], v[236:237], off
	global_load_dwordx4 v[8:11], v[240:241], off
	global_load_dwordx4 v[12:15], v[242:243], off
	s_waitcnt vmcnt(3)
	ds_write_b128 v238, v[0:3]
	s_waitcnt vmcnt(2)
	ds_write_b128 v238, v[4:7] offset:4096
	s_waitcnt vmcnt(1)
	ds_write_b128 v238, v[8:11] offset:8192
	s_waitcnt vmcnt(0)
	ds_write_b128 v238, v[12:15] offset:12288
	s_waitcnt lgkmcnt(0)
	s_barrier
	ds_read_b32 v195, v16
	v_add_u32_e32 v16, 0, v188
	ds_read_b128 v[34:37], v16 offset:16384
	v_bfrev_b32_e32 v0, 1
	s_waitcnt lgkmcnt(1)
	v_cndmask_b32_e64 v46, v195, 0, s[48:49]
	v_cmp_neq_f32_e64 s[0:1], 0, v46
	s_nop 1
	v_cndmask_b32_e64 v0, v0, v46, s[0:1]
	v_mov_b32_e32 v1, v0
	v_mov_b32_e32 v2, v0
	v_mov_b32_e32 v3, v0
	v_mov_b32_e32 v4, v0
	v_mov_b32_e32 v5, v0
	v_mov_b32_e32 v6, v0
	v_mov_b32_e32 v7, v0
	v_mov_b32_e32 v8, v0
	v_mov_b32_e32 v9, v0
	v_mov_b32_e32 v10, v0
	v_mov_b32_e32 v11, v0
	v_mov_b32_e32 v12, v0
	v_mov_b32_e32 v13, v0
	v_mov_b32_e32 v14, v0
	v_mov_b32_e32 v15, v0
	s_waitcnt lgkmcnt(0)
	s_nop 0
	v_mfma_f32_32x32x16_bf16 v[18:33], v[34:37], v[128:131], v[0:15]
	ds_read_b128 v[34:37], v16 offset:24576
	v_or_b32_e32 v16, 32, v48
	v_xad_u32 v196, v16, v47, v39
	v_mov_b64_e32 v[16:17], v[14:15]
	v_add_u32_e32 v49, 0, v196
	s_nop 1
	v_mov_b64_e32 v[14:15], v[12:13]
	v_mov_b64_e32 v[12:13], v[10:11]
	v_mov_b64_e32 v[10:11], v[8:9]
	v_mov_b64_e32 v[8:9], v[6:7]
	v_mov_b64_e32 v[6:7], v[4:5]
	v_mov_b64_e32 v[4:5], v[2:3]
	v_mov_b64_e32 v[2:3], v[0:1]
	v_or_b32_e32 v1, 64, v48
	v_xad_u32 v190, v1, v47, v39
	s_waitcnt lgkmcnt(0)
	v_mfma_f32_32x32x16_bf16 v[2:17], v[34:37], v[128:131], v[2:17]
	ds_read_b128 v[34:37], v49 offset:16384
	v_add_u32_e32 v1, 0, v190
	s_waitcnt lgkmcnt(0)
	v_mfma_f32_32x32x16_bf16 v[18:33], v[34:37], v[132:135], v[18:33]
	ds_read_b128 v[34:37], v49 offset:24576
	s_waitcnt lgkmcnt(0)
	v_mfma_f32_32x32x16_bf16 v[2:17], v[34:37], v[132:135], v[2:17]
	ds_read_b128 v[34:37], v1 offset:16384
	s_waitcnt lgkmcnt(0)
	v_mfma_f32_32x32x16_bf16 v[18:33], v[34:37], v[136:139], v[18:33]
	ds_read_b128 v[34:37], v1 offset:24576
	v_or_b32_e32 v1, 0x60, v48
	v_xad_u32 v189, v1, v47, v39
	v_add_u32_e32 v1, 0, v189
	s_waitcnt lgkmcnt(0)
	v_mfma_f32_32x32x16_bf16 v[2:17], v[34:37], v[136:139], v[2:17]
	ds_read_b128 v[34:37], v1 offset:16384
	s_waitcnt lgkmcnt(0)
	v_mfma_f32_32x32x16_bf16 v[18:33], v[34:37], v[140:143], v[18:33]
	ds_read_b128 v[34:37], v1 offset:24576
	v_mov_b32_e32 v1, s34
	ds_read_b32 v200, v1
	s_waitcnt lgkmcnt(1)
	v_mfma_f32_32x32x16_bf16 v[2:17], v[34:37], v[140:143], v[2:17]
	s_cbranch_vccnz .LBB0_159
	v_lshlrev_b32_e32 v1, 2, v185
	s_mov_b64 s[56:57], 0

; __device__ __forceinline__ float max3f(float a, float b, float c) { float r; asm("v_max3_f32 %0, %1, %2, %3" : "=v"(r) : "v"(a), "v"(b), "v"(c)); return r; }
; #define SLOAD(i, k0) do { sr_[i].vs0 = ld8(&Vg[(long)((k0) + sr) * LDP + sc]); sr_[i].vs1 = ld8(&Vg[(long)((k0) + 32 + sr) * LDP + sc]); \
;     sr_[i].ks0 = ld8(&Kg[(long)((k0) + sr) * LDP + sc]); sr_[i].ks1 = ld8(&Kg[(long)((k0) + 32 + sr) * LDP + sc]); } while (0)
; #define SWRITE(off, i) do { *(bf16x8*)(V_lds + (off) + vst0) = sr_[i].vs0;          \
;     *(bf16x8*)(V_lds + (off) + vst1) = sr_[i].vs1; int kc = sc * 2;               \
;     *(bf16x8*)(K_lds + (off) + KSWZ(sr, kc)) = sr_[i].ks0;                       \
;     *(bf16x8*)(K_lds + (off) + KSWZ(32 + sr, kc)) = sr_[i].ks1; } while (0)
; #define SWAIT() asm volatile("s_waitcnt vmcnt(0)" ::: "memory")
; template <bool FIRST> __device__ __forceinline__ void partialSM2(f32x16& p0, f32x16& p1, float& m_ref, f32x16& negm, float& alpha) {
;   float pmax = max3f(p0[0], p0[1], p1[0]), pmb = max3f(p0[2], p0[3], p1[1]);
;   pmax = max3f(pmax, p1[2], p1[3]);
; #pragma unroll
;   for (int r = 4; r < 16; r += 4) { pmax = max3f(pmax, p0[r], p0[r + 1]); pmb = max3f(pmb, p0[r + 2], p0[r + 3]); pmax = max3f(pmax, p1[r], p1[r + 1]); pmb = max3f(pmb, p1[r + 2], p1[r + 3]); }
;   pmax = max3f(pmax, pmb, pmb);
;   { auto rr = __builtin_amdgcn_permlane32_swap(__float_as_uint(pmax), __float_as_uint(pmax), false, false);
;     pmax = fmaxf(__uint_as_float(rr[0]), __uint_as_float(rr[1])); }
;   alpha = 1.f;
;   if (FIRST || !__builtin_expect(__all(pmax <= THR), 1)) {
;     const float dl = FIRST ? pmax : fmaxf(pmax, 0.f); m_ref += dl; if (!FIRST) alpha = __builtin_amdgcn_exp2f(-dl);
; #pragma unroll
;     for (int r = 0; r < 16; ++r) { p0[r] -= dl; p1[r] -= dl; negm[r] -= dl; }
;   }
; #pragma unroll
;   for (int r = 0; r < 16; ++r) p0[r] = __builtin_amdgcn_exp2f(p0[r]);
; }
; template <int MODE, int ORD> ...
;     ...
;   SLOAD(SO, KVBLK);
;   SWAIT(); SWRITE(SLOT, SO); __syncthreads();
.LBB0_162:
	v_and_b32_e32 v1, 63, v40
	v_lshlrev_b32_e32 v35, 4, v1
	v_lshlrev_b32_e32 v34, 3, v1
	v_and_b32_e32 v35, 0xc0, v35
	v_lshlrev_b32_e32 v36, 1, v1
	v_and_or_b32 v35, v34, 24, v35
	v_and_b32_e32 v36, 32, v36
	v_and_b32_e32 v34, 0x100, v34
	s_cmp_lg_u32 0, -1
	v_or3_b32 v34, v35, v36, v34
	s_cselect_b32 s34, 0, 0
	v_add_u32_e32 v199, s34, v34
	v_max3_f32 v34, v18, v19, v2
	v_max3_f32 v35, v20, v21, v3
	v_cndmask_b32_e64 v214, 0, v46, s[0:1]
	v_max3_f32 v34, v34, v4, v5
	v_max3_f32 v35, v35, v24, v25
	s_and_b32 s0, s63, 0x3fffffc0
	v_max3_f32 v34, v34, v22, v23
	v_max3_f32 v35, v35, v8, v9
	s_lshl_b32 s0, s0, 2
	v_max3_f32 v34, v34, v6, v7
	v_max3_f32 v35, v35, v28, v29
	v_add_u32_e32 v36, 0x60, v38
	v_max3_f32 v34, v34, v26, v27
	s_add_i32 s49, s0, 0
	v_max3_f32 v58, v34, v10, v11
	v_add_u32_e32 v34, 64, v38
	v_max3_f32 v59, v35, v12, v13
	v_mad_i64_i32 v[34:35], s[0:1], v34, s73, 0
	v_mad_i64_i32 v[36:37], s[0:1], v36, s73, 0
	v_or_b32_e32 v34, v34, v41
	v_or_b32_e32 v36, v36, v41
	v_lshlrev_b64 v[50:51], 1, v[34:35]
	v_lshlrev_b64 v[52:53], 1, v[36:37]
	v_lshl_add_u64 v[34:35], s[42:43], 0, v[50:51]
	v_lshl_add_u64 v[46:47], s[42:43], 0, v[52:53]
	v_lshl_add_u64 v[50:51], s[18:19], 0, v[50:51]
	v_lshl_add_u64 v[54:55], s[18:19], 0, v[52:53]
	s_mov_b64 s[100:101], 0x90000
	v_lshl_add_u64 v[234:235], v[234:235], 0, s[100:101]
	v_lshl_add_u64 v[236:237], v[236:237], 0, s[100:101]
	v_lshl_add_u64 v[240:241], v[240:241], 0, s[100:101]
	v_lshl_add_u64 v[242:243], v[242:243], 0, s[100:101]
	global_load_dwordx4 v[34:37], v[234:235], off
	global_load_dwordx4 v[46:49], v[236:237], off
	global_load_dwordx4 v[50:53], v[240:241], off
	global_load_dwordx4 v[54:57], v[242:243], off
	v_max3_f32 v41, v58, v30, v31
	v_max3_f32 v58, v59, v32, v33
	s_add_i32 s68, s68, s79
	v_max3_f32 v41, v41, v14, v15
	v_max3_f32 v58, v58, v16, v17
	v_ashrrev_i32_e32 v39, 31, v38
	v_max3_f32 v41, v41, v58, v58
	v_cmp_gt_u32_e64 s[0:1], 32, v1
	v_mov_b32_e32 v58, v41
	s_nop 1
	v_permlane32_swap_b32_e32 v41, v58
	v_max_f32_e32 v58, v58, v58
	v_max_f32_e32 v41, v41, v41
	v_max_f32_e32 v41, v41, v58
	v_sub_f32_e32 v64, v0, v41
	v_add_u32_e32 v0, s68, v184
	v_sub_f32_e32 v81, v3, v41
	v_sub_f32_e32 v80, v2, v41
	v_sub_u32_e32 v202, v197, v0
	v_lshl_add_u64 v[0:1], s[10:11], 0, v[38:39]
	v_mov_b32_e32 v2, s78
	v_mov_b32_e32 v3, v205
	v_mad_u64_u32 v[2:3], s[10:11], v0, s53, v[2:3]
	v_mov_b32_e32 v0, v3
	v_sub_f32_e32 v18, v18, v41
	v_sub_f32_e32 v19, v19, v41
	v_sub_f32_e32 v20, v20, v41
	v_sub_f32_e32 v21, v21, v41
	v_sub_f32_e32 v22, v22, v41
	v_sub_f32_e32 v23, v23, v41
	v_sub_f32_e32 v24, v24, v41
	v_sub_f32_e32 v25, v25, v41
	v_sub_f32_e32 v26, v26, v41
	v_sub_f32_e32 v27, v27, v41
	v_sub_f32_e32 v28, v28, v41
	v_sub_f32_e32 v29, v29, v41
	v_sub_f32_e32 v30, v30, v41
	v_sub_f32_e32 v31, v31, v41
	v_sub_f32_e32 v32, v32, v41
	v_sub_f32_e32 v33, v33, v41
	v_mad_u64_u32 v[0:1], s[10:11], v1, s53, v[0:1]
	v_exp_f32_e32 v173, v18
	v_exp_f32_e32 v175, v19
	v_exp_f32_e32 v171, v20
	v_exp_f32_e32 v174, v21
	v_exp_f32_e32 v169, v22
	v_exp_f32_e32 v172, v23
	v_exp_f32_e32 v168, v24
	v_exp_f32_e32 v170, v25
	v_exp_f32_e32 v165, v26
	v_exp_f32_e32 v167, v27
	v_exp_f32_e32 v163, v28
	v_exp_f32_e32 v166, v29
	v_exp_f32_e32 v161, v30
	v_exp_f32_e32 v164, v31
	v_exp_f32_e32 v160, v32
	v_exp_f32_e32 v162, v33
	v_and_b32_e32 v1, 15, v40
	v_readlane_b32 s10, v255, 31
	v_sub_f32_e32 v93, v15, v41
	v_sub_f32_e32 v92, v14, v41
	s_waitcnt vmcnt(0)
	v_lshl_or_b32 v2, v1, 4, v2
	v_mov_b32_e32 v3, v0
	v_readlane_b32 s11, v255, 32
	v_mov_b32_e32 v14, v205
	v_mov_b32_e32 v15, v205
	s_add_i32 s49, s49, 0x18000
	v_sub_f32_e32 v95, v17, v41
	v_sub_f32_e32 v94, v16, v41
	v_sub_f32_e32 v91, v13, v41
	v_sub_f32_e32 v90, v12, v41
	v_sub_f32_e32 v89, v11, v41
	v_sub_f32_e32 v88, v10, v41
	v_sub_f32_e32 v87, v9, v41
	v_sub_f32_e32 v86, v8, v41
	v_sub_f32_e32 v85, v7, v41
	v_sub_f32_e32 v84, v6, v41
	v_sub_f32_e32 v83, v5, v41
	v_sub_f32_e32 v82, v4, v41
	s_waitcnt vmcnt(3)
	ds_write_b128 v238, v[34:37] offset:32768
	s_waitcnt vmcnt(2)
	ds_write_b128 v238, v[46:49] offset:36864
	s_waitcnt vmcnt(1)
	ds_write_b128 v238, v[50:53] offset:40960
	s_waitcnt vmcnt(0)
	ds_write_b128 v238, v[54:57] offset:45056
	v_lshl_add_u64 v[176:177], s[10:11], 0, v[2:3]
	s_cmp_lt_i32 s62, 4
	s_cselect_b32 s100, 0, 0xfffdc800
	s_cselect_b32 s101, 0, -1
	v_lshl_add_u64 v[176:177], v[176:177], 0, s[100:101]
	v_mov_b32_e32 v0, v205
	v_mov_b32_e32 v1, v205
	v_mov_b32_e32 v2, v205
	v_mov_b32_e32 v3, v205
	v_mov_b32_e32 v4, v205
	v_mov_b32_e32 v5, v205
	v_mov_b32_e32 v6, v205
	v_mov_b32_e32 v7, v205
	v_mov_b32_e32 v8, v205
	v_mov_b32_e32 v9, v205
	v_mov_b32_e32 v10, v205
	v_mov_b32_e32 v11, v205
	v_mov_b32_e32 v12, v205
	v_mov_b32_e32 v13, v205
	v_mov_b64_e32 v[62:63], v[14:15]
	v_mov_b64_e32 v[46:47], v[14:15]
	v_mov_b64_e32 v[30:31], v[14:15]
	s_mov_b32 s56, 0
	s_mov_b32 s57, 2
	v_mov_b32_e32 v65, v64
	v_mov_b32_e32 v66, v64
	v_mov_b32_e32 v67, v64
	v_mov_b32_e32 v68, v64
	v_mov_b32_e32 v69, v64
	v_mov_b32_e32 v70, v64
	v_mov_b32_e32 v71, v64
	v_mov_b32_e32 v72, v64
	v_mov_b32_e32 v73, v64
	v_mov_b32_e32 v74, v64
	v_mov_b32_e32 v75, v64
	v_mov_b32_e32 v76, v64
	v_mov_b32_e32 v77, v64
	v_mov_b32_e32 v78, v64
	v_mov_b32_e32 v79, v64
	s_add_i32 s19, s92, 0x9f
	v_lshl_add_u32 v186, v184, 2, s49
	s_sub_i32 s42, 0, s68
	v_mov_b32_e32 v187, 0
	v_mov_b32_e32 v203, 1.0
	s_mov_b32 s18, 0x10000
	s_mov_b32 s43, 0x8000
	v_mov_b64_e32 v[60:61], v[12:13]
	v_mov_b64_e32 v[58:59], v[10:11]
	v_mov_b64_e32 v[56:57], v[8:9]
	v_mov_b64_e32 v[54:55], v[6:7]
	v_mov_b64_e32 v[52:53], v[4:5]
	v_mov_b64_e32 v[50:51], v[2:3]
	v_mov_b64_e32 v[48:49], v[0:1]
	v_mov_b64_e32 v[44:45], v[12:13]
	v_mov_b64_e32 v[42:43], v[10:11]
	v_mov_b64_e32 v[40:41], v[8:9]
	v_mov_b64_e32 v[38:39], v[6:7]
	v_mov_b64_e32 v[36:37], v[4:5]
	v_mov_b64_e32 v[34:35], v[2:3]
	v_mov_b64_e32 v[32:33], v[0:1]
	v_mov_b64_e32 v[28:29], v[12:13]
	v_mov_b64_e32 v[26:27], v[10:11]
	v_mov_b64_e32 v[24:25], v[8:9]
	v_mov_b64_e32 v[22:23], v[6:7]
	v_mov_b64_e32 v[20:21], v[4:5]
	v_mov_b64_e32 v[18:19], v[2:3]
	v_mov_b64_e32 v[16:17], v[0:1]
	s_mov_b32 s10, 0
	s_waitcnt lgkmcnt(0)
	s_barrier
.LBB0_163:
	s_mov_b32 s68, s43
	s_mov_b32 s43, s10
	s_add_i32 s78, s42, s56
	s_add_i32 s34, s56, 64
	s_add_i32 s35, s78, 0x7f
	s_cmpk_gt_i32 s35, 0xff80
	s_cselect_b64 s[10:11], -1, 0
	s_cmp_lt_u32 s34, s19
	s_cselect_b64 s[80:81], -1, 0
	s_and_b64 s[10:11], s[10:11], s[80:81]
	s_cmpk_lt_i32 s35, 0xff81
	s_cselect_b64 vcc, -1, 0
	v_cndmask_b32_e32 v96, v200, v195, vcc
	v_cndmask_b32_e64 v215, v96, 0, s[10:11]
	v_cmp_eq_f32_e32 vcc, v215, v214
	s_cbranch_vccnz .LBB0_165
	v_sub_f32_e32 v96, v215, v214
	v_pk_add_f32 v[78:79], v[78:79], v[96:97] op_sel_hi:[1,0]
	v_pk_add_f32 v[76:77], v[76:77], v[96:97] op_sel_hi:[1,0]
	v_pk_add_f32 v[74:75], v[74:75], v[96:97] op_sel_hi:[1,0]
	v_pk_add_f32 v[72:73], v[72:73], v[96:97] op_sel_hi:[1,0]
	v_pk_add_f32 v[70:71], v[70:71], v[96:97] op_sel_hi:[1,0]
	v_pk_add_f32 v[68:69], v[68:69], v[96:97] op_sel_hi:[1,0]
	v_pk_add_f32 v[66:67], v[66:67], v[96:97] op_sel_hi:[1,0]
	v_pk_add_f32 v[64:65], v[64:65], v[96:97] op_sel_hi:[1,0]
	s_branch .LBB0_166

; __device__ __forceinline__ unsigned cvtpk(float lo, float hi) { unsigned r; asm volatile("v_cvt_pk_bf16_f32 %0, %1, %2" : "=v"(r) : "v"(lo), "v"(hi)); return r; }
; __device__ __forceinline__ void finishSM(f32x16& p0, f32x16& p1, float alpha, float& l_reg, bf16x8& pa0, bf16x8& pa1, bf16x8& pa2, bf16x8& pa3) {
; #pragma unroll
;   for (int r = 0; r < 16; ++r) p1[r] = __builtin_amdgcn_exp2f(p1[r]);
;   float ps = 0;
; #pragma unroll
;   for (int r = 0; r < 16; ++r) ps += p0[r];
; #pragma unroll
;   for (int r = 0; r < 16; ++r) ps += p1[r];
;   { auto rr = __builtin_amdgcn_permlane32_swap(__float_as_uint(ps), __float_as_uint(ps), false, false);
;     ps = __uint_as_float(rr[0]) + __uint_as_float(rr[1]); }
;   l_reg = l_reg * alpha + ps;
;     ...
;   PK4(p0, 0, pa0); PK4(p0, 8, pa1); PK4(p1, 0, pa2); PK4(p1, 8, pa3);
;     ...
; }
; __device__ __forceinline__ bf16x8 scale_bf16x8(bf16x8 v, float c) {
;   u32x4 w = *reinterpret_cast<u32x4*>(&v), o;
; #pragma unroll
;   for (int i = 0; i < 4; ++i) { const float lo = __uint_as_float(w[i] << 16), hh = __uint_as_float(w[i] & 0xffff0000u); o[i] = cvtpk(lo * c, hh * c); }
;   return *reinterpret_cast<bf16x8*>(&o);
; }
; template <int ND0> __device__ __forceinline__ void qkt(f32x16& p0, f32x16& p1, const char* Ks, const bf16x8* qr, int r32, int hi, int cboff, const f32x16& ci) {
; #pragma unroll
;   for (int d0 = 0; d0 < ND0; ++d0) { int cb = cboff + (d0 * 16 + hi * 8) * 2;
;     bf16x8 b0 = *reinterpret_cast<const bf16x8*>(Ks + KSWZ(r32, cb));
;     bf16x8 b1 = *reinterpret_cast<const bf16x8*>(Ks + KSWZ(32 + r32, cb));
;     if (d0 == 0) { p0 = __builtin_amdgcn_mfma_f32_32x32x16_bf16(b0, qr[0], ci, 0, 0, 0); p1 = __builtin_amdgcn_mfma_f32_32x32x16_bf16(b1, qr[0], ci, 0, 0, 0); }
;     else { p0 = __builtin_amdgcn_mfma_f32_32x32x16_bf16(b0, qr[d0], p0, 0, 0, 0); p1 = __builtin_amdgcn_mfma_f32_32x32x16_bf16(b1, qr[d0], p1, 0, 0, 0); } }
; }
.LBB0_166:
	s_add_i32 s34, s68, 0
	v_add_u32_e32 v96, s34, v188
	ds_read_b128 v[210:213], v96 offset:24576
	ds_read_b128 v[96:99], v96 offset:16384
	v_add_u32_e32 v201, s34, v196
	ds_read_b128 v[148:151], v201 offset:24576
	ds_read_b128 v[144:147], v201 offset:16384
	v_add_u32_e32 v201, s34, v190
	ds_read_b128 v[156:159], v201 offset:24576
	ds_read_b128 v[152:155], v201 offset:16384
	v_add_u32_e32 v201, s34, v189
	ds_read_b128 v[240:243], v201 offset:24576
	ds_read_b128 v[234:237], v201 offset:16384
	v_exp_f32_e32 v206, v81
	v_exp_f32_e32 v207, v82
	v_exp_f32_e32 v208, v83
	v_exp_f32_e32 v209, v84
	v_exp_f32_e32 v87, v87
	v_exp_f32_e32 v214, v88
	v_exp_f32_e32 v220, v93
	v_exp_f32_e32 v221, v94
	v_exp_f32_e32 v95, v95
	v_exp_f32_e32 v201, v80
	v_exp_f32_e32 v216, v89
	v_exp_f32_e32 v217, v90
	v_exp_f32_e32 v218, v91
	v_exp_f32_e32 v219, v92
	v_add_f32_e32 v80, 0, v173
	v_add_f32_e32 v80, v175, v80
	v_add_f32_e32 v80, v171, v80
	v_add_f32_e32 v80, v174, v80
	v_add_f32_e32 v80, v169, v80
	v_add_f32_e32 v80, v172, v80
	v_add_f32_e32 v80, v168, v80
	v_add_f32_e32 v80, v170, v80
	v_add_f32_e32 v80, v165, v80
	v_add_f32_e32 v80, v167, v80
	v_add_f32_e32 v80, v163, v80
	v_add_f32_e32 v80, v166, v80
	v_add_f32_e32 v80, v161, v80
	v_add_f32_e32 v80, v164, v80
	v_add_f32_e32 v80, v160, v80
	v_add_f32_e32 v80, v162, v80
	v_add_f32_e32 v80, v201, v80
	s_waitcnt lgkmcnt(6)
	v_mfma_f32_32x32x16_bf16 v[112:127], v[96:99], v[128:131], v[64:79]
	v_add_f32_e32 v80, v206, v80
	v_add_f32_e32 v80, v207, v80
	v_add_f32_e32 v80, v208, v80
	v_add_f32_e32 v80, v209, v80
	v_mfma_f32_32x32x16_bf16 v[96:111], v[210:213], v[128:131], v[64:79]
	v_exp_f32_e32 v212, v85
	v_exp_f32_e32 v213, v86
	s_waitcnt lgkmcnt(4)
	v_mfma_f32_32x32x16_bf16 v[112:127], v[144:147], v[132:135], v[112:127]
	v_add_f32_e32 v80, v212, v80
	v_add_f32_e32 v80, v213, v80
	v_add_f32_e32 v80, v87, v80
	v_mfma_f32_32x32x16_bf16 v[96:111], v[148:151], v[132:135], v[96:111]
	v_add_f32_e32 v80, v214, v80
	v_add_f32_e32 v80, v216, v80
	v_add_f32_e32 v80, v217, v80
	s_waitcnt lgkmcnt(2)
	v_mfma_f32_32x32x16_bf16 v[112:127], v[152:155], v[136:139], v[112:127]
	v_add_f32_e32 v80, v218, v80
	v_add_f32_e32 v80, v219, v80
	v_add_f32_e32 v80, v220, v80
	v_mfma_f32_32x32x16_bf16 v[96:111], v[156:159], v[136:139], v[96:111]
	s_mov_b64 s[100:101], 0x24000
	v_lshl_add_u64 v[144:145], v[176:177], 0, s[100:101]
	s_mov_b32 s100, 0x48000
	v_lshl_add_u64 v[156:157], v[176:177], 0, s[100:101]
	s_mov_b32 s100, 0x6c000
	v_lshl_add_u64 v[148:149], v[176:177], 0, s[100:101]
	global_load_dwordx4 v[152:155], v[176:177], off
	global_load_dwordx4 v[144:147], v[144:145], off
	global_load_dwordx4 v[156:159], v[156:157], off
	global_load_dwordx4 v[148:151], v[148:149], off
	v_add_f32_e32 v80, v221, v80
	v_add_f32_e32 v210, v95, v80
	v_mov_b32_e32 v211, v210
	s_waitcnt lgkmcnt(1)
	v_mfma_f32_32x32x16_bf16 v[96:111], v[240:243], v[140:143], v[96:111]
	v_cvt_pk_bf16_f32 v80, v173, v175
	v_cvt_pk_bf16_f32 v81, v171, v174
	v_cvt_pk_bf16_f32 v82, v169, v172
	v_cvt_pk_bf16_f32 v83, v168, v170
	v_cvt_pk_bf16_f32 v88, v165, v167
	v_cvt_pk_bf16_f32 v89, v163, v166
	v_cvt_pk_bf16_f32 v90, v161, v164
	v_cvt_pk_bf16_f32 v91, v160, v162
	s_waitcnt lgkmcnt(0)
	v_mfma_f32_32x32x16_bf16 v[112:127], v[234:237], v[140:143], v[112:127]
	v_cvt_pk_bf16_f32 v84, v201, v206
	v_cvt_pk_bf16_f32 v85, v207, v208
	v_cvt_pk_bf16_f32 v86, v209, v212
	v_cvt_pk_bf16_f32 v87, v213, v87
	v_cvt_pk_bf16_f32 v92, v214, v216
	v_cvt_pk_bf16_f32 v93, v217, v218
	v_cvt_pk_bf16_f32 v94, v219, v220
	v_cvt_pk_bf16_f32 v95, v221, v95
	s_nop 1
	v_permlane32_swap_b32_e32 v210, v211
	v_permlane32_swap_b32_e32 v80, v82
	v_permlane32_swap_b32_e32 v81, v83
	v_permlane32_swap_b32_e32 v88, v90
	v_permlane32_swap_b32_e32 v89, v91
	v_permlane32_swap_b32_e32 v84, v86
	v_permlane32_swap_b32_e32 v85, v87
	v_permlane32_swap_b32_e32 v92, v94
	v_permlane32_swap_b32_e32 v93, v95
	s_andn2_b64 vcc, exec, s[10:11]
	v_add_u32_e32 v212, s56, v202
	s_cbranch_vccnz .LBB0_168
	v_add_u32_e32 v160, 0xc0, v212
	v_med3_i32 v161, v160, 0, v249
	v_med3_i32 v160, v160, s75, v250
	v_lshl_add_u32 v162, v160, 2, s69
	v_add_u32_e32 v160, 0xc1, v212
	v_med3_i32 v163, v160, 0, v249
	v_med3_i32 v160, v160, s75, v250
	v_lshl_add_u32 v164, v160, 2, s69
	v_add_u32_e32 v160, 0xc2, v212
	v_med3_i32 v165, v160, 0, v249
	v_med3_i32 v160, v160, s75, v250
	v_lshl_add_u32 v166, v160, 2, s69
	v_add_u32_e32 v160, 0xc3, v212
	v_med3_i32 v167, v160, 0, v249
	v_med3_i32 v160, v160, s75, v250
	v_lshl_add_u32 v161, v161, 2, s69
	v_lshl_add_u32 v163, v163, 2, s69
	v_lshl_add_u32 v165, v165, 2, s69
	v_lshl_add_u32 v167, v167, 2, s69
	v_lshl_add_u32 v168, v160, 2, s69
	ds_read_b32 v160, v161
	ds_read_b32 v162, v162 offset:128
	ds_read_b32 v161, v163
	ds_read_b32 v163, v164 offset:128
	ds_read_b32 v164, v165
	ds_read_b32 v166, v166 offset:128
	ds_read_b32 v165, v167
	ds_read_b32 v167, v168 offset:128
	v_add_u32_e32 v168, 0xc8, v212
	v_med3_i32 v169, v168, 0, v249
	v_med3_i32 v168, v168, s75, v250
	v_lshl_add_u32 v170, v168, 2, s69
	v_add_u32_e32 v168, 0xc9, v212
	v_med3_i32 v171, v168, 0, v249
	v_med3_i32 v168, v168, s75, v250
	v_lshl_add_u32 v172, v168, 2, s69
	v_add_u32_e32 v168, 0xca, v212
	v_med3_i32 v173, v168, 0, v249
	v_med3_i32 v168, v168, s75, v250
	v_add_u32_e32 v207, 0xd1, v212
	v_lshl_add_u32 v174, v168, 2, s69
	v_add_u32_e32 v168, 0xcb, v212
	v_med3_i32 v208, v207, 0, v249
	v_med3_i32 v207, v207, s75, v250
	v_med3_i32 v175, v168, 0, v249
	v_med3_i32 v168, v168, s75, v250
	v_lshl_add_u32 v213, v207, 2, s69
	v_add_u32_e32 v207, 0xd2, v212
	v_lshl_add_u32 v169, v169, 2, s69
	v_lshl_add_u32 v171, v171, 2, s69
	v_lshl_add_u32 v173, v173, 2, s69
	v_lshl_add_u32 v175, v175, 2, s69
	v_lshl_add_u32 v201, v168, 2, s69
	v_lshl_add_u32 v209, v208, 2, s69
	v_med3_i32 v208, v207, 0, v249
	v_med3_i32 v207, v207, s75, v250
	ds_read_b32 v168, v169
	ds_read_b32 v170, v170 offset:128
	ds_read_b32 v169, v171
	ds_read_b32 v171, v172 offset:128
	ds_read_b32 v172, v173
	ds_read_b32 v174, v174 offset:128
	ds_read_b32 v173, v175
	ds_read_b32 v175, v201 offset:128
	v_add_u32_e32 v201, 0xd0, v212
	v_lshl_add_u32 v217, v207, 2, s69
	v_add_u32_e32 v207, 0xd3, v212
	v_med3_i32 v206, v201, 0, v249
	v_lshl_add_u32 v214, v208, 2, s69
	v_med3_i32 v208, v207, 0, v249
	v_med3_i32 v201, v201, s75, v250
	v_lshl_add_u32 v206, v206, 2, s69
	v_med3_i32 v207, v207, s75, v250
	v_lshl_add_u32 v219, v208, 2, s69
	v_lshl_add_u32 v201, v201, 2, s69
	v_lshl_add_u32 v220, v207, 2, s69
	ds_read_b32 v206, v206
	ds_read_b32 v208, v201 offset:128
	ds_read_b32 v207, v209
	ds_read_b32 v209, v213 offset:128
	ds_read_b32 v216, v214
	ds_read_b32 v218, v217 offset:128
	ds_read_b32 v217, v219
	ds_read_b32 v219, v220 offset:128
	v_add_u32_e32 v214, 0xd9, v212
	v_med3_i32 v220, v214, 0, v249
	v_lshl_add_u32 v221, v220, 2, s69
	v_add_u32_e32 v220, 0xda, v212
	v_med3_i32 v222, v220, 0, v249
	v_med3_i32 v220, v220, s75, v250
	v_add_u32_e32 v201, 0xd8, v212
	v_lshl_add_u32 v226, v220, 2, s69
	v_add_u32_e32 v220, 0xdb, v212
	v_med3_i32 v213, v201, 0, v249
	v_lshl_add_u32 v223, v222, 2, s69
	v_med3_i32 v222, v220, 0, v249
	v_med3_i32 v220, v220, s75, v250
	v_med3_i32 v201, v201, s75, v250
	v_lshl_add_u32 v213, v213, 2, s69
	v_med3_i32 v214, v214, s75, v250
	v_lshl_add_u32 v225, v222, 2, s69
	v_lshl_add_u32 v227, v220, 2, s69
	v_lshl_add_u32 v201, v201, 2, s69
	v_lshl_add_u32 v214, v214, 2, s69
	ds_read_b32 v220, v213
	ds_read_b32 v222, v201 offset:128
	ds_read_b32 v224, v223
	ds_read_b32 v225, v225
	ds_read_b32 v221, v221
	ds_read_b32 v227, v227 offset:128
	ds_read_b32 v226, v226 offset:128
	ds_read_b32 v223, v214 offset:128
	s_waitcnt lgkmcnt(4)
	v_pk_add_f32 v[126:127], v[126:127], v[224:225]
	s_waitcnt lgkmcnt(3)
	v_pk_add_f32 v[124:125], v[124:125], v[220:221]
	v_pk_add_f32 v[122:123], v[122:123], v[216:217]
	v_pk_add_f32 v[120:121], v[120:121], v[206:207]
	v_pk_add_f32 v[118:119], v[118:119], v[172:173]
	v_pk_add_f32 v[116:117], v[116:117], v[168:169]
	v_pk_add_f32 v[114:115], v[114:115], v[164:165]
	v_pk_add_f32 v[112:113], v[112:113], v[160:161]
	s_waitcnt lgkmcnt(1)
	v_pk_add_f32 v[110:111], v[110:111], v[226:227]
	s_waitcnt lgkmcnt(0)
	v_pk_add_f32 v[108:109], v[108:109], v[222:223]
	v_pk_add_f32 v[106:107], v[106:107], v[218:219]
	v_pk_add_f32 v[104:105], v[104:105], v[208:209]
	v_pk_add_f32 v[102:103], v[102:103], v[174:175]
	v_pk_add_f32 v[100:101], v[100:101], v[170:171]
	v_pk_add_f32 v[98:99], v[98:99], v[166:167]
	v_pk_add_f32 v[96:97], v[96:97], v[162:163]

; #define SBAR() __builtin_amdgcn_sched_barrier(0)
; #define VRD8(D0, L0, H0, L1, H1, L2, H2, L3, H3) do { L0 = tr_read<v_rd_off(D0, 0, 0)>(vb); H0 = tr_read<v_rd_off(D0, 0, 1)>(vb); L1 = tr_read<v_rd_off(D0, 1, 0)>(vb); H1 = tr_read<v_rd_off(D0, 1, 1)>(vb); \
;     L2 = tr_read<v_rd_off(D0, 2, 0)>(vb); H2 = tr_read<v_rd_off(D0, 2, 1)>(vb); L3 = tr_read<v_rd_off(D0, 3, 0)>(vb); H3 = tr_read<v_rd_off(D0, 3, 1)>(vb); } while (0)
; #define MMA4(OD, L0, H0, L1, H1, L2, H2, L3, H3) do { OD = __builtin_amdgcn_mfma_f32_32x32x16_bf16(pa0, PK(L0, H0), OD, 0, 0, 0); OD = __builtin_amdgcn_mfma_f32_32x32x16_bf16(pa1, PK(L1, H1), OD, 0, 0, 0); \
;     OD = __builtin_amdgcn_mfma_f32_32x32x16_bf16(pa2, PK(L2, H2), OD, 0, 0, 0); OD = __builtin_amdgcn_mfma_f32_32x32x16_bf16(pa3, PK(L3, H3), OD, 0, 0, 0); } while (0)
; __device__ __forceinline__ void pv_partial(f32x16* o, int vb, bf16x8 pa0, bf16x8 pa1, bf16x8 pa2, bf16x8 pa3, f32x16& p0, f32x16& p1, float& m_ref, f32x16& negm, float& alpha) {
;     ...
;   VRD8(3, b0, b1, b2, b3, b4, b5, b6, b7);
;   asm volatile("s_waitcnt lgkmcnt(8)" ::: "memory"); SBAR();
;   MMA4(o[2], a0, a1, a2, a3, a4, a5, a6, a7);
; #pragma unroll
;   for (int r = 0; r < 8; ++r) p0[r] = __builtin_amdgcn_exp2f(p0[r]);
;   SBAR();
;   asm volatile("s_waitcnt lgkmcnt(0)" ::: "memory"); SBAR();
;   MMA4(o[3], b0, b1, b2, b3, b4, b5, b6, b7);
; #pragma unroll
;   for (int r = 8; r < 16; ++r) p0[r] = __builtin_amdgcn_exp2f(p0[r]);
.LBB0_170:
	ds_read_b64_tr_b16 v[216:217], v201 offset:0x600
	ds_read_b64_tr_b16 v[218:219], v201 offset:0xe00
	ds_read_b64_tr_b16 v[220:221], v201 offset:0x1600
	ds_read_b64_tr_b16 v[222:223], v201 offset:0x1e00
	ds_read_b64_tr_b16 v[224:225], v201 offset:0x2600
	ds_read_b64_tr_b16 v[226:227], v201 offset:0x2e00
	ds_read_b64_tr_b16 v[228:229], v201 offset:0x3600
	ds_read_b64_tr_b16 v[230:231], v201 offset:0x3e00
	s_waitcnt lgkmcnt(8)
	v_mfma_f32_32x32x16_bf16 v[32:47], v[80:83], v[172:175], v[32:47]
	v_exp_f32_e32 v172, v116
	v_exp_f32_e32 v173, v117
	v_exp_f32_e32 v174, v118
	v_exp_f32_e32 v175, v119
	v_mfma_f32_32x32x16_bf16 v[32:47], v[88:91], v[168:171], v[32:47]
	v_exp_f32_e32 v168, v112
	v_exp_f32_e32 v169, v113
	v_exp_f32_e32 v170, v114
	v_exp_f32_e32 v171, v115
	v_mfma_f32_32x32x16_bf16 v[32:47], v[84:87], v[164:167], v[32:47]
	v_exp_f32_e32 v206, v120
	v_exp_f32_e32 v207, v121
	v_mfma_f32_32x32x16_bf16 v[32:47], v[92:95], v[160:163], v[32:47]
	v_exp_f32_e32 v208, v122
	v_exp_f32_e32 v209, v123
	s_waitcnt lgkmcnt(0)
	v_mfma_f32_32x32x16_bf16 v[16:31], v[80:83], v[216:219], v[16:31]
	v_exp_f32_e32 v217, v124
	v_exp_f32_e32 v218, v125
	v_exp_f32_e32 v219, v126
	s_add_i32 s79, s18, 0
	v_add_u32_e32 v80, s79, v238
	s_waitcnt vmcnt(0)
	ds_write_b128 v80, v[152:155]
	ds_write_b128 v80, v[144:147] offset:4096
	v_mfma_f32_32x32x16_bf16 v[16:31], v[88:91], v[220:223], v[16:31]
	v_exp_f32_e32 v220, v127
	ds_write_b128 v80, v[156:159] offset:8192
	v_cmp_gt_f32_e32 vcc, 1.0, v213
	ds_write_b128 v80, v[148:151] offset:12288
	v_mfma_f32_32x32x16_bf16 v[16:31], v[84:87], v[224:227], v[16:31]
	v_mfma_f32_32x32x16_bf16 v[16:31], v[92:95], v[228:231], v[16:31]
	s_cbranch_vccz .LBB0_174
	s_and_saveexec_b64 s[10:11], s[0:1]
	ds_write_b32 v186, v213 offset:128
	s_or_b64 exec, exec, s[10:11]
	s_waitcnt lgkmcnt(0)
	v_add_u32_e32 v92, s49, v204
	ds_read_b128 v[80:83], v92 offset:224
	ds_read_b128 v[84:87], v92 offset:192
	ds_read_b128 v[88:91], v92 offset:160
	ds_read_b128 v[92:95], v92 offset:128
	s_waitcnt lgkmcnt(3)
	v_pk_mul_f32 v[12:13], v[12:13], v[80:81]
	s_waitcnt lgkmcnt(2)
	v_pk_mul_f32 v[8:9], v[8:9], v[84:85]
	s_waitcnt lgkmcnt(1)
	v_pk_mul_f32 v[4:5], v[4:5], v[88:89]
	v_pk_mul_f32 v[14:15], v[14:15], v[82:83]
	v_pk_mul_f32 v[10:11], v[10:11], v[86:87]
	v_pk_mul_f32 v[6:7], v[6:7], v[90:91]
	s_waitcnt lgkmcnt(0)
	v_pk_mul_f32 v[2:3], v[2:3], v[94:95]
	v_pk_mul_f32 v[0:1], v[0:1], v[92:93]
	v_pk_mul_f32 v[60:61], v[60:61], v[80:81]
	v_pk_mul_f32 v[56:57], v[56:57], v[84:85]
	v_pk_mul_f32 v[52:53], v[52:53], v[88:89]
	v_pk_mul_f32 v[62:63], v[62:63], v[82:83]
	v_pk_mul_f32 v[58:59], v[58:59], v[86:87]
	v_pk_mul_f32 v[54:55], v[54:55], v[90:91]
	v_pk_mul_f32 v[50:51], v[50:51], v[94:95]
	v_pk_mul_f32 v[48:49], v[48:49], v[92:93]
	v_pk_mul_f32 v[44:45], v[44:45], v[80:81]
	v_pk_mul_f32 v[40:41], v[40:41], v[84:85]
	v_pk_mul_f32 v[36:37], v[36:37], v[88:89]
	v_pk_mul_f32 v[46:47], v[46:47], v[82:83]
	v_pk_mul_f32 v[42:43], v[42:43], v[86:87]
	v_pk_mul_f32 v[38:39], v[38:39], v[90:91]
	v_pk_mul_f32 v[34:35], v[34:35], v[94:95]
	v_pk_mul_f32 v[32:33], v[32:33], v[92:93]
	v_pk_mul_f32 v[28:29], v[28:29], v[80:81]
	v_pk_mul_f32 v[24:25], v[24:25], v[84:85]
	v_pk_mul_f32 v[20:21], v[20:21], v[88:89]
	v_pk_mul_f32 v[30:31], v[30:31], v[82:83]
	v_pk_mul_f32 v[26:27], v[26:27], v[86:87]
	v_pk_mul_f32 v[22:23], v[22:23], v[90:91]
	v_pk_mul_f32 v[18:19], v[18:19], v[94:95]
	v_pk_mul_f32 v[16:17], v[16:17], v[92:93]
.LBB0_174:
	s_addk_i32 s56, 0x80
	s_waitcnt lgkmcnt(0)
	s_barrier
	s_addk_i32 s78, 0xbf
	s_cmpk_gt_i32 s78, 0xff80
	s_cselect_b64 s[10:11], -1, 0
	s_cmp_lt_u32 s56, s19
	s_cselect_b64 s[80:81], -1, 0
	s_and_b64 s[10:11], s[10:11], s[80:81]
	s_cmpk_lt_i32 s78, 0xff81
	s_cselect_b64 vcc, -1, 0
	v_cndmask_b32_e32 v80, v200, v195, vcc
	v_cndmask_b32_e64 v214, v80, 0, s[10:11]
	v_cmp_eq_f32_e32 vcc, v214, v215
	s_cbranch_vccnz .LBB0_176
	v_sub_f32_e32 v80, v214, v215
	v_pk_add_f32 v[78:79], v[80:81], v[78:79] op_sel_hi:[0,1]
	v_pk_add_f32 v[76:77], v[80:81], v[76:77] op_sel_hi:[0,1]
	v_pk_add_f32 v[74:75], v[80:81], v[74:75] op_sel_hi:[0,1]
	v_pk_add_f32 v[72:73], v[80:81], v[72:73] op_sel_hi:[0,1]
	v_pk_add_f32 v[70:71], v[80:81], v[70:71] op_sel_hi:[0,1]
	v_pk_add_f32 v[68:69], v[80:81], v[68:69] op_sel_hi:[0,1]
	v_pk_add_f32 v[66:67], v[80:81], v[66:67] op_sel_hi:[0,1]
	v_pk_add_f32 v[64:65], v[80:81], v[64:65] op_sel_hi:[0,1]
	s_branch .LBB0_177

; __device__ __forceinline__ unsigned cvtpk(float lo, float hi) { unsigned r; asm volatile("v_cvt_pk_bf16_f32 %0, %1, %2" : "=v"(r) : "v"(lo), "v"(hi)); return r; }
; __device__ __forceinline__ void finishSM(f32x16& p0, f32x16& p1, float alpha, float& l_reg, bf16x8& pa0, bf16x8& pa1, bf16x8& pa2, bf16x8& pa3) {
; #pragma unroll
;   for (int r = 0; r < 16; ++r) p1[r] = __builtin_amdgcn_exp2f(p1[r]);
;   float ps = 0;
; #pragma unroll
;   for (int r = 0; r < 16; ++r) ps += p0[r];
; #pragma unroll
;   for (int r = 0; r < 16; ++r) ps += p1[r];
;   { auto rr = __builtin_amdgcn_permlane32_swap(__float_as_uint(ps), __float_as_uint(ps), false, false);
;     ps = __uint_as_float(rr[0]) + __uint_as_float(rr[1]); }
;   l_reg = l_reg * alpha + ps;
;     ...
;   PK4(p0, 0, pa0); PK4(p0, 8, pa1); PK4(p1, 0, pa2); PK4(p1, 8, pa3);
;     ...
; }
; __device__ __forceinline__ bf16x8 scale_bf16x8(bf16x8 v, float c) {
;   u32x4 w = *reinterpret_cast<u32x4*>(&v), o;
; #pragma unroll
;   for (int i = 0; i < 4; ++i) { const float lo = __uint_as_float(w[i] << 16), hh = __uint_as_float(w[i] & 0xffff0000u); o[i] = cvtpk(lo * c, hh * c); }
;   return *reinterpret_cast<bf16x8*>(&o);
; }
; template <int ND0> __device__ __forceinline__ void qkt(f32x16& p0, f32x16& p1, const char* Ks, const bf16x8* qr, int r32, int hi, int cboff, const f32x16& ci) {
; #pragma unroll
;   for (int d0 = 0; d0 < ND0; ++d0) { int cb = cboff + (d0 * 16 + hi * 8) * 2;
;     bf16x8 b0 = *reinterpret_cast<const bf16x8*>(Ks + KSWZ(r32, cb));
;     bf16x8 b1 = *reinterpret_cast<const bf16x8*>(Ks + KSWZ(32 + r32, cb));
;     if (d0 == 0) { p0 = __builtin_amdgcn_mfma_f32_32x32x16_bf16(b0, qr[0], ci, 0, 0, 0); p1 = __builtin_amdgcn_mfma_f32_32x32x16_bf16(b1, qr[0], ci, 0, 0, 0); }
;     else { p0 = __builtin_amdgcn_mfma_f32_32x32x16_bf16(b0, qr[d0], p0, 0, 0, 0); p1 = __builtin_amdgcn_mfma_f32_32x32x16_bf16(b1, qr[d0], p1, 0, 0, 0); } }
; }
.LBB0_177:
	v_add_u32_e32 v80, s79, v188
	ds_read_b128 v[160:163], v80 offset:24576
	ds_read_b128 v[80:83], v80 offset:16384
	v_add_u32_e32 v164, s79, v196
	ds_read_b128 v[148:151], v164 offset:24576
	ds_read_b128 v[144:147], v164 offset:16384
	v_add_u32_e32 v164, s79, v190
	ds_read_b128 v[156:159], v164 offset:24576
	ds_read_b128 v[152:155], v164 offset:16384
	v_add_u32_e32 v164, s79, v189
	ds_read_b128 v[240:243], v164 offset:24576
	ds_read_b128 v[234:237], v164 offset:16384
	v_exp_f32_e32 v96, v96
	v_exp_f32_e32 v97, v97
	v_exp_f32_e32 v98, v98
	v_exp_f32_e32 v99, v99
	v_exp_f32_e32 v100, v100
	v_exp_f32_e32 v101, v101
	v_exp_f32_e32 v102, v102
	v_exp_f32_e32 v103, v103
	v_add_f32_e32 v252, 0, v168
	v_add_f32_e32 v252, v169, v252
	v_add_f32_e32 v252, v170, v252
	v_add_f32_e32 v252, v171, v252
	v_add_f32_e32 v252, v172, v252
	v_add_f32_e32 v252, v173, v252
	v_add_f32_e32 v252, v174, v252
	v_add_f32_e32 v252, v175, v252
	v_add_f32_e32 v252, v206, v252
	v_add_f32_e32 v252, v207, v252
	v_add_f32_e32 v252, v208, v252
	v_add_f32_e32 v252, v209, v252
	v_add_f32_e32 v252, v217, v252
	v_add_f32_e32 v252, v218, v252
	v_add_f32_e32 v252, v219, v252
	v_add_f32_e32 v252, v220, v252
	v_add_f32_e32 v252, v96, v252
	v_add_f32_e32 v252, v97, v252
	v_add_f32_e32 v252, v98, v252
	v_add_f32_e32 v252, v99, v252
	v_add_f32_e32 v252, v100, v252
	v_add_f32_e32 v252, v101, v252
	v_add_f32_e32 v252, v102, v252
	v_add_f32_e32 v252, v103, v252
	s_waitcnt lgkmcnt(6)
	v_mfma_f32_32x32x16_bf16 v[112:127], v[80:83], v[128:131], v[64:79]
	v_mfma_f32_32x32x16_bf16 v[80:95], v[160:163], v[128:131], v[64:79]
	v_exp_f32_e32 v160, v104
	v_exp_f32_e32 v161, v105
	v_exp_f32_e32 v162, v106
	v_exp_f32_e32 v163, v107
	s_waitcnt lgkmcnt(4)
	v_mfma_f32_32x32x16_bf16 v[80:95], v[148:151], v[132:135], v[80:95]
	v_exp_f32_e32 v164, v108
	v_exp_f32_e32 v165, v109
	v_mfma_f32_32x32x16_bf16 v[112:127], v[144:147], v[132:135], v[112:127]
	v_exp_f32_e32 v166, v110
	v_exp_f32_e32 v167, v111
	v_add_f32_e32 v252, v160, v252
	s_waitcnt lgkmcnt(2)
	v_mfma_f32_32x32x16_bf16 v[80:95], v[156:159], v[136:139], v[80:95]
	v_add_f32_e32 v252, v161, v252
	v_add_f32_e32 v252, v162, v252
	v_add_f32_e32 v252, v163, v252
	v_mfma_f32_32x32x16_bf16 v[112:127], v[152:155], v[136:139], v[112:127]
	s_mov_b64 s[100:101], 0x90000
	v_lshl_add_u64 v[152:153], v[176:177], 0, s[100:101]
	s_mov_b32 s100, 0xb4000
	v_lshl_add_u64 v[144:145], v[176:177], 0, s[100:101]
	s_mov_b32 s100, 0xd8000
	v_lshl_add_u64 v[156:157], v[176:177], 0, s[100:101]
	s_mov_b32 s100, 0xfc000
	v_lshl_add_u64 v[148:149], v[176:177], 0, s[100:101]
	global_load_dwordx4 v[152:155], v[152:153], off
	global_load_dwordx4 v[144:147], v[144:145], off
	global_load_dwordx4 v[156:159], v[156:157], off
	global_load_dwordx4 v[148:151], v[148:149], off
	v_add_f32_e32 v252, v164, v252
	v_add_f32_e32 v252, v165, v252
	v_add_f32_e32 v252, v166, v252
	v_add_f32_e32 v215, v167, v252
	v_mov_b32_e32 v216, v215
	s_waitcnt lgkmcnt(1)
	v_mfma_f32_32x32x16_bf16 v[80:95], v[240:243], v[140:143], v[80:95]
	v_cvt_pk_bf16_f32 v104, v168, v169
	v_cvt_pk_bf16_f32 v105, v170, v171
	v_cvt_pk_bf16_f32 v106, v172, v173
	v_cvt_pk_bf16_f32 v107, v174, v175
	v_cvt_pk_bf16_f32 v108, v206, v207
	v_cvt_pk_bf16_f32 v109, v208, v209
	v_cvt_pk_bf16_f32 v110, v217, v218
	v_cvt_pk_bf16_f32 v111, v219, v220
	s_waitcnt lgkmcnt(0)
	v_mfma_f32_32x32x16_bf16 v[112:127], v[234:237], v[140:143], v[112:127]
	v_cvt_pk_bf16_f32 v96, v96, v97
	v_cvt_pk_bf16_f32 v97, v98, v99
	v_cvt_pk_bf16_f32 v98, v100, v101
	v_cvt_pk_bf16_f32 v99, v102, v103
	v_cvt_pk_bf16_f32 v100, v160, v161
	v_cvt_pk_bf16_f32 v101, v162, v163
	v_cvt_pk_bf16_f32 v102, v164, v165
	v_cvt_pk_bf16_f32 v103, v166, v167
	s_nop 1
	v_permlane32_swap_b32_e32 v215, v216
	v_permlane32_swap_b32_e32 v104, v106
	v_permlane32_swap_b32_e32 v105, v107
	v_permlane32_swap_b32_e32 v108, v110
	v_permlane32_swap_b32_e32 v109, v111
	v_permlane32_swap_b32_e32 v96, v98
	v_permlane32_swap_b32_e32 v97, v99
	v_permlane32_swap_b32_e32 v100, v102
	v_permlane32_swap_b32_e32 v101, v103
	s_andn2_b64 vcc, exec, s[10:11]
	s_cbranch_vccnz .LBB0_179
	v_add_u32_e32 v160, 0x100, v212
	v_med3_i32 v161, v160, 0, v249
	v_med3_i32 v160, v160, s75, v250
	v_lshl_add_u32 v162, v160, 2, s69
	v_add_u32_e32 v160, 0x101, v212
	v_med3_i32 v163, v160, 0, v249
	v_med3_i32 v160, v160, s75, v250
	v_lshl_add_u32 v164, v160, 2, s69
	v_add_u32_e32 v160, 0x102, v212
	v_med3_i32 v165, v160, 0, v249
	v_med3_i32 v160, v160, s75, v250
	v_lshl_add_u32 v166, v160, 2, s69
	v_add_u32_e32 v160, 0x103, v212
	v_med3_i32 v167, v160, 0, v249
	v_med3_i32 v160, v160, s75, v250
	v_lshl_add_u32 v161, v161, 2, s69
	v_lshl_add_u32 v163, v163, 2, s69
	v_lshl_add_u32 v165, v165, 2, s69
	v_lshl_add_u32 v167, v167, 2, s69
	v_lshl_add_u32 v168, v160, 2, s69
	ds_read_b32 v160, v161
	ds_read_b32 v162, v162 offset:128
	ds_read_b32 v161, v163
	ds_read_b32 v163, v164 offset:128
	ds_read_b32 v164, v165
	ds_read_b32 v166, v166 offset:128
	ds_read_b32 v165, v167
	ds_read_b32 v167, v168 offset:128
	v_add_u32_e32 v168, 0x108, v212
	v_med3_i32 v169, v168, 0, v249
	v_med3_i32 v168, v168, s75, v250
	v_lshl_add_u32 v170, v168, 2, s69
	v_add_u32_e32 v168, 0x109, v212
	v_med3_i32 v171, v168, 0, v249
	v_med3_i32 v168, v168, s75, v250
	v_lshl_add_u32 v172, v168, 2, s69
	v_add_u32_e32 v168, 0x10a, v212
	v_med3_i32 v173, v168, 0, v249
	v_med3_i32 v168, v168, s75, v250
	v_lshl_add_u32 v174, v168, 2, s69
	v_add_u32_e32 v168, 0x10b, v212
	v_med3_i32 v175, v168, 0, v249
	v_med3_i32 v168, v168, s75, v250
	v_lshl_add_u32 v169, v169, 2, s69
	v_lshl_add_u32 v171, v171, 2, s69
	v_lshl_add_u32 v173, v173, 2, s69
	v_lshl_add_u32 v175, v175, 2, s69
	v_lshl_add_u32 v206, v168, 2, s69
	ds_read_b32 v168, v169
	ds_read_b32 v170, v170 offset:128
	ds_read_b32 v169, v171
	ds_read_b32 v171, v172 offset:128
	ds_read_b32 v172, v173
	ds_read_b32 v174, v174 offset:128
	ds_read_b32 v173, v175
	ds_read_b32 v175, v206 offset:128
	v_add_u32_e32 v206, 0x110, v212
	v_med3_i32 v207, v206, 0, v249
	v_med3_i32 v206, v206, s75, v250
	v_lshl_add_u32 v208, v206, 2, s69
	v_add_u32_e32 v206, 0x111, v212
	v_med3_i32 v209, v206, 0, v249
	v_med3_i32 v206, v206, s75, v250
	v_lshl_add_u32 v217, v206, 2, s69
	v_add_u32_e32 v206, 0x112, v212
	v_med3_i32 v218, v206, 0, v249
	v_med3_i32 v206, v206, s75, v250
	v_lshl_add_u32 v219, v206, 2, s69
	v_add_u32_e32 v206, 0x113, v212
	v_add_u32_e32 v223, 0x119, v212
	v_med3_i32 v220, v206, 0, v249
	v_med3_i32 v224, v223, 0, v249
	v_med3_i32 v223, v223, s75, v250
	v_lshl_add_u32 v207, v207, 2, s69
	v_lshl_add_u32 v209, v209, 2, s69
	v_lshl_add_u32 v218, v218, 2, s69
	v_med3_i32 v206, v206, s75, v250
	v_lshl_add_u32 v221, v220, 2, s69
	v_lshl_add_u32 v230, v223, 2, s69
	v_add_u32_e32 v223, 0x11a, v212
	v_lshl_add_u32 v222, v206, 2, s69
	ds_read_b32 v206, v207
	ds_read_b32 v208, v208 offset:128
	ds_read_b32 v207, v209
	ds_read_b32 v209, v217 offset:128
	ds_read_b32 v218, v218
	ds_read_b32 v220, v219 offset:128
	ds_read_b32 v219, v221
	ds_read_b32 v221, v222 offset:128
	v_add_u32_e32 v217, 0x118, v212
	v_lshl_add_u32 v225, v224, 2, s69
	v_med3_i32 v224, v223, 0, v249
	v_med3_i32 v223, v223, s75, v250
	v_add_u32_e32 v212, 0x11b, v212
	v_med3_i32 v222, v217, 0, v249
	v_lshl_add_u32 v228, v223, 2, s69
	v_med3_i32 v223, v212, 0, v249
	v_med3_i32 v217, v217, s75, v250
	v_lshl_add_u32 v222, v222, 2, s69
	v_lshl_add_u32 v226, v224, 2, s69
	v_med3_i32 v212, v212, s75, v250
	v_lshl_add_u32 v223, v223, 2, s69
	v_lshl_add_u32 v217, v217, 2, s69
	v_lshl_add_u32 v212, v212, 2, s69
	ds_read_b32 v222, v222
	ds_read_b32 v224, v217 offset:128
	ds_read_b32 v226, v226
	ds_read_b32 v227, v223
	ds_read_b32 v223, v225
	ds_read_b32 v229, v212 offset:128
	ds_read_b32 v228, v228 offset:128
	ds_read_b32 v225, v230 offset:128
	s_waitcnt lgkmcnt(4)
	v_pk_add_f32 v[126:127], v[126:127], v[226:227]
	s_waitcnt lgkmcnt(3)
	v_pk_add_f32 v[124:125], v[124:125], v[222:223]
	v_pk_add_f32 v[122:123], v[122:123], v[218:219]
	v_pk_add_f32 v[120:121], v[120:121], v[206:207]
	v_pk_add_f32 v[118:119], v[118:119], v[172:173]
	v_pk_add_f32 v[116:117], v[116:117], v[168:169]
	v_pk_add_f32 v[114:115], v[114:115], v[164:165]
	v_pk_add_f32 v[112:113], v[112:113], v[160:161]
	s_waitcnt lgkmcnt(1)
	v_pk_add_f32 v[94:95], v[94:95], v[228:229]
	s_waitcnt lgkmcnt(0)
	v_pk_add_f32 v[92:93], v[92:93], v[224:225]
	v_pk_add_f32 v[90:91], v[90:91], v[220:221]
	v_pk_add_f32 v[88:89], v[88:89], v[208:209]
	v_pk_add_f32 v[86:87], v[86:87], v[174:175]
	v_pk_add_f32 v[84:85], v[84:85], v[170:171]
	v_pk_add_f32 v[82:83], v[82:83], v[166:167]
	v_pk_add_f32 v[80:81], v[80:81], v[162:163]

; #define SBAR() __builtin_amdgcn_sched_barrier(0)
; #define VRD8(D0, L0, H0, L1, H1, L2, H2, L3, H3) do { L0 = tr_read<v_rd_off(D0, 0, 0)>(vb); H0 = tr_read<v_rd_off(D0, 0, 1)>(vb); L1 = tr_read<v_rd_off(D0, 1, 0)>(vb); H1 = tr_read<v_rd_off(D0, 1, 1)>(vb); \
;     L2 = tr_read<v_rd_off(D0, 2, 0)>(vb); H2 = tr_read<v_rd_off(D0, 2, 1)>(vb); L3 = tr_read<v_rd_off(D0, 3, 0)>(vb); H3 = tr_read<v_rd_off(D0, 3, 1)>(vb); } while (0)
; #define MMA4(OD, L0, H0, L1, H1, L2, H2, L3, H3) do { OD = __builtin_amdgcn_mfma_f32_32x32x16_bf16(pa0, PK(L0, H0), OD, 0, 0, 0); OD = __builtin_amdgcn_mfma_f32_32x32x16_bf16(pa1, PK(L1, H1), OD, 0, 0, 0); \
;     OD = __builtin_amdgcn_mfma_f32_32x32x16_bf16(pa2, PK(L2, H2), OD, 0, 0, 0); OD = __builtin_amdgcn_mfma_f32_32x32x16_bf16(pa3, PK(L3, H3), OD, 0, 0, 0); } while (0)
; __device__ __forceinline__ void pv_partial(f32x16* o, int vb, bf16x8 pa0, bf16x8 pa1, bf16x8 pa2, bf16x8 pa3, f32x16& p0, f32x16& p1, float& m_ref, f32x16& negm, float& alpha) {
;     ...
;   VRD8(3, b0, b1, b2, b3, b4, b5, b6, b7);
;   asm volatile("s_waitcnt lgkmcnt(8)" ::: "memory"); SBAR();
;   MMA4(o[2], a0, a1, a2, a3, a4, a5, a6, a7);
; #pragma unroll
;   for (int r = 0; r < 8; ++r) p0[r] = __builtin_amdgcn_exp2f(p0[r]);
;   SBAR();
;   asm volatile("s_waitcnt lgkmcnt(0)" ::: "memory"); SBAR();
;   MMA4(o[3], b0, b1, b2, b3, b4, b5, b6, b7);
; #pragma unroll
;   for (int r = 8; r < 16; ++r) p0[r] = __builtin_amdgcn_exp2f(p0[r]);
.LBB0_181:
	ds_read_b64_tr_b16 v[218:219], v217 offset:0x600
	ds_read_b64_tr_b16 v[220:221], v217 offset:0xe00
	ds_read_b64_tr_b16 v[222:223], v217 offset:0x1600
	ds_read_b64_tr_b16 v[224:225], v217 offset:0x1e00
	ds_read_b64_tr_b16 v[226:227], v217 offset:0x2600
	ds_read_b64_tr_b16 v[228:229], v217 offset:0x2e00
	ds_read_b64_tr_b16 v[230:231], v217 offset:0x3600
	ds_read_b64_tr_b16 v[232:233], v217 offset:0x3e00
	s_waitcnt lgkmcnt(8)
	v_mfma_f32_32x32x16_bf16 v[32:47], v[104:107], v[172:175], v[32:47]
	v_exp_f32_e32 v173, v112
	v_exp_f32_e32 v175, v113
	v_exp_f32_e32 v174, v115
	v_exp_f32_e32 v172, v117
	v_mfma_f32_32x32x16_bf16 v[32:47], v[108:111], v[168:171], v[32:47]
	v_exp_f32_e32 v171, v114
	v_exp_f32_e32 v169, v116
	v_exp_f32_e32 v168, v118
	v_exp_f32_e32 v170, v119
	v_mfma_f32_32x32x16_bf16 v[32:47], v[96:99], v[164:167], v[32:47]
	v_exp_f32_e32 v165, v120
	v_exp_f32_e32 v167, v121
	v_exp_f32_e32 v166, v123
	v_exp_f32_e32 v164, v125
	v_mfma_f32_32x32x16_bf16 v[32:47], v[100:103], v[160:163], v[32:47]
	v_exp_f32_e32 v163, v122
	v_exp_f32_e32 v161, v124
	v_exp_f32_e32 v160, v126
	v_exp_f32_e32 v162, v127
	s_waitcnt lgkmcnt(0)
	v_mfma_f32_32x32x16_bf16 v[16:31], v[104:107], v[218:221], v[16:31]
	s_add_i32 s78, s43, 0
	s_waitcnt vmcnt(0)
	v_add_u32_e32 v104, s78, v238
	ds_write_b128 v104, v[152:155]
	v_cmp_gt_f32_e32 vcc, 1.0, v212
	v_mfma_f32_32x32x16_bf16 v[16:31], v[108:111], v[222:225], v[16:31]
	v_mfma_f32_32x32x16_bf16 v[16:31], v[96:99], v[226:229], v[16:31]
	ds_write_b128 v104, v[144:147] offset:4096
	ds_write_b128 v104, v[156:159] offset:8192
	ds_write_b128 v104, v[148:151] offset:12288
	v_mfma_f32_32x32x16_bf16 v[16:31], v[100:103], v[230:233], v[16:31]
	s_cbranch_vccz .LBB0_185
	s_and_saveexec_b64 s[10:11], s[0:1]
	ds_write_b32 v186, v212 offset:128
	s_or_b64 exec, exec, s[10:11]
	s_waitcnt lgkmcnt(0)
	v_add_u32_e32 v108, s49, v204
	ds_read_b128 v[96:99], v108 offset:224
	ds_read_b128 v[100:103], v108 offset:192
	ds_read_b128 v[104:107], v108 offset:160
	ds_read_b128 v[108:111], v108 offset:128
	s_waitcnt lgkmcnt(3)
	v_pk_mul_f32 v[12:13], v[12:13], v[96:97]
	s_waitcnt lgkmcnt(2)
	v_pk_mul_f32 v[8:9], v[8:9], v[100:101]
	s_waitcnt lgkmcnt(1)
	v_pk_mul_f32 v[4:5], v[4:5], v[104:105]
	v_pk_mul_f32 v[14:15], v[14:15], v[98:99]
	v_pk_mul_f32 v[10:11], v[10:11], v[102:103]
	v_pk_mul_f32 v[6:7], v[6:7], v[106:107]
	s_waitcnt lgkmcnt(0)
	v_pk_mul_f32 v[2:3], v[2:3], v[110:111]
	v_pk_mul_f32 v[0:1], v[0:1], v[108:109]
	v_pk_mul_f32 v[60:61], v[60:61], v[96:97]
	v_pk_mul_f32 v[56:57], v[56:57], v[100:101]
	v_pk_mul_f32 v[52:53], v[52:53], v[104:105]
	v_pk_mul_f32 v[62:63], v[62:63], v[98:99]
	v_pk_mul_f32 v[58:59], v[58:59], v[102:103]
	v_pk_mul_f32 v[54:55], v[54:55], v[106:107]
	v_pk_mul_f32 v[50:51], v[50:51], v[110:111]
	v_pk_mul_f32 v[48:49], v[48:49], v[108:109]
	v_pk_mul_f32 v[44:45], v[44:45], v[96:97]
	v_pk_mul_f32 v[40:41], v[40:41], v[100:101]
	v_pk_mul_f32 v[36:37], v[36:37], v[104:105]
	v_pk_mul_f32 v[46:47], v[46:47], v[98:99]
	v_pk_mul_f32 v[42:43], v[42:43], v[102:103]
	v_pk_mul_f32 v[38:39], v[38:39], v[106:107]
	v_pk_mul_f32 v[34:35], v[34:35], v[110:111]
	v_pk_mul_f32 v[32:33], v[32:33], v[108:109]
	v_pk_mul_f32 v[28:29], v[28:29], v[96:97]
	v_pk_mul_f32 v[24:25], v[24:25], v[100:101]
	v_pk_mul_f32 v[20:21], v[20:21], v[104:105]
	v_pk_mul_f32 v[30:31], v[30:31], v[98:99]
	v_pk_mul_f32 v[26:27], v[26:27], v[102:103]
	v_pk_mul_f32 v[22:23], v[22:23], v[106:107]
	v_pk_mul_f32 v[18:19], v[18:19], v[110:111]
	v_pk_mul_f32 v[16:17], v[16:17], v[108:109]
.LBB0_185:
	v_add_f32_e32 v96, v210, v211
	v_fmac_f32_e32 v96, v203, v187
	v_add_f32_e32 v187, v215, v216
	s_add_i32 s57, s57, 2
	s_mov_b64 s[10:11], 0x120000
	v_fmac_f32_e32 v187, v96, v213
	s_cmp_ge_u32 s57, s67
	v_lshl_add_u64 v[176:177], v[176:177], 0, s[10:11]
	s_waitcnt lgkmcnt(0)
	s_barrier
	s_cbranch_scc1 .LBB0_189
	s_mov_b32 s10, s18
	s_mov_b32 s18, s68
	v_mov_b32_e32 v203, v212
	s_branch .LBB0_163

; __global__ void __launch_bounds__(NWAVES * 64, 2) mega_fwd(Args args) {
	.amdhsa_kernel _Z8mega_fwd4Args
		.amdhsa_group_segment_fixed_size 0
		.amdhsa_private_segment_fixed_size 0
		.amdhsa_kernarg_size 408
		.amdhsa_user_sgpr_count 2
		.amdhsa_user_sgpr_dispatch_ptr 0
		.amdhsa_user_sgpr_queue_ptr 0
		.amdhsa_user_sgpr_kernarg_segment_ptr 1
		.amdhsa_user_sgpr_dispatch_id 0
		.amdhsa_user_sgpr_kernarg_preload_length 0
		.amdhsa_user_sgpr_kernarg_preload_offset 0
		.amdhsa_user_sgpr_private_segment_size 0
		.amdhsa_uses_dynamic_stack 0
		.amdhsa_enable_private_segment 0
		.amdhsa_system_sgpr_workgroup_id_x 1
		.amdhsa_system_sgpr_workgroup_id_y 0
		.amdhsa_system_sgpr_workgroup_id_z 0
		.amdhsa_system_sgpr_workgroup_info 0
		.amdhsa_system_vgpr_workitem_id 2
		.amdhsa_next_free_vgpr 256
		.amdhsa_next_free_sgpr 102
		.amdhsa_accum_offset 256
		.amdhsa_reserve_vcc 1
		.amdhsa_float_round_mode_32 0
		.amdhsa_float_round_mode_16_64 0
		.amdhsa_float_denorm_mode_32 3
		.amdhsa_float_denorm_mode_16_64 3
		.amdhsa_dx10_clamp 1
		.amdhsa_ieee_mode 1
		.amdhsa_fp16_overflow 0
		.amdhsa_tg_split 0
		.amdhsa_exception_fp_ieee_invalid_op 0
		.amdhsa_exception_fp_denorm_src 0
		.amdhsa_exception_fp_ieee_div_zero 0
		.amdhsa_exception_fp_ieee_overflow 0
		.amdhsa_exception_fp_ieee_underflow 0
		.amdhsa_exception_fp_ieee_inexact 0
		.amdhsa_exception_int_div_zero 0
	.end_amdhsa_kernel

; __global__ void __launch_bounds__(NWAVES * 64, 2) mega_fwd(Args args) {
amdhsa.kernels:
  - .agpr_count:     0
    .args:
      - .offset:         0
        .size:           152
        .value_kind:     by_value
      - .offset:         152
        .size:           4
        .value_kind:     hidden_block_count_x
      - .offset:         156
        .size:           4
        .value_kind:     hidden_block_count_y
      - .offset:         160
        .size:           4
        .value_kind:     hidden_block_count_z
      - .offset:         164
        .size:           2
        .value_kind:     hidden_group_size_x
      - .offset:         166
        .size:           2
        .value_kind:     hidden_group_size_y
      - .offset:         168
        .size:           2
        .value_kind:     hidden_group_size_z
      - .offset:         170
        .size:           2
        .value_kind:     hidden_remainder_x
      - .offset:         172
        .size:           2
        .value_kind:     hidden_remainder_y
      - .offset:         174
        .size:           2
        .value_kind:     hidden_remainder_z
      - .offset:         192
        .size:           8
        .value_kind:     hidden_global_offset_x
      - .offset:         200
        .size:           8
        .value_kind:     hidden_global_offset_y
      - .offset:         208
        .size:           8
        .value_kind:     hidden_global_offset_z
      - .offset:         216
        .size:           2
        .value_kind:     hidden_grid_dims
      - .offset:         240
        .size:           8
        .value_kind:     hidden_multigrid_sync_arg
      - .offset:         272
        .size:           4
        .value_kind:     hidden_dynamic_lds_size
    .group_segment_fixed_size: 0
    .kernarg_segment_align: 8
    .kernarg_segment_size: 408
    .language:       OpenCL C
    .language_version:
      - 2
      - 0
    .max_flat_workgroup_size: 512
    .name:           _Z8mega_fwd4Args
    .private_segment_fixed_size: 0
    .sgpr_count:     108
    .sgpr_spill_count: 119
    .symbol:         _Z8mega_fwd4Args.kd
    .uniform_work_group_size: 1
    .uses_dynamic_stack: false
    .vgpr_count:     256
    .vgpr_spill_count: 0
    .wavefront_size: 64
